# nt cache policy on the once-read f32 residual loads of the attention out-projection epilogue, stacked on v82
# speedup vs baseline: 1.0094x; 1.0094x over previous
; #define EPI_GET(dst, ai, bj, m, s) do { _Pragma("unroll") for (int e_ = 0; e_ < 4; ++e_) { (dst)[e_] = acc[ai][bj][m][0][e_] * (s); (dst)[4 + e_] = acc[ai][bj][m][1][e_] * (s); } } while (0)
;     __device__ __forceinline__ void row(const f32x4 (&acc)[2][2][4][2], int ai, int m, int r, int rl, bool samp, int c8, int fq, const float* a, const float* b) const {
;         float lo[8], hi[8]; EPI_GET(lo, ai, 0, m, 1.f); EPI_GET(hi, ai, 1, m, 1.f);
;         float s2 = 0.f;
; #pragma unroll
;         for (int e = 0; e < 8; ++e) { lo[e] += a[e]; hi[e] += b[e]; s2 += lo[e] * lo[e] + hi[e] * hi[e]; }
;         if (dstP) { float* dp = (samp ? dstS : dstP) + (size_t)rl * 1024 + c8; store8_f32(dp, lo); store8_f32(dp + 128, hi); }
;         if (dstB) { store8_bf16(dstB + (size_t)r * 1024 + c8, lo); store8_bf16(dstB + (size_t)r * 1024 + c8 + 128, hi); }
;         if (ss) { s2 += __shfl_xor(s2, 16); s2 += __shfl_xor(s2, 32); if (fq == 0) atomicAdd(ss + r, s2); }
;     __device__ __forceinline__ void operator()(const f32x4 (&acc)[2][2][4][2], const Unit& u, int wr, int wc, int fr, int fq) const {
;     ...
; #pragma unroll
;             for (int ai = 0; ai < 2; ++ai) {
;                 f32x4 fa[4][2], fb[4][2];
; #pragma unroll
;                 for (int m = 0; m < 4; ++m) { const int r = EPI_ROWS(ai, m); const int rl = samp ? r - MP : r; const float* rp = (samp ? resS : resP) + (size_t)rl * 1024 + c8;
;                     fa[m][0] = *(const f32x4*)rp; fa[m][1] = *(const f32x4*)(rp + 4); fb[m][0] = *(const f32x4*)(rp + 128); fb[m][1] = *(const f32x4*)(rp + 132); }
; #pragma unroll
;                 for (int m = 0; m < 4; ++m) { const int r = EPI_ROWS(ai, m); const int rl = samp ? r - MP : r;
;                     const float a[8] = {fa[m][0].x, fa[m][0].y, fa[m][0].z, fa[m][0].w, fa[m][1].x, fa[m][1].y, fa[m][1].z, fa[m][1].w};
;                     const float b[8] = {fb[m][0].x, fb[m][0].y, fb[m][0].z, fb[m][0].w, fb[m][1].x, fb[m][1].y, fb[m][1].z, fb[m][1].w};
;                     row(acc, ai, m, r, rl, samp, c8, fq, a, b); }
.LBB0_2890:
	s_cmp_gt_i32 s6, 63
	v_lshl_add_u32 v194, s6, 8, v204
	s_cselect_b64 vcc, -1, 0
	v_add_u32_e32 v128, 0xffffc000, v194
	s_and_b64 s[6:7], vcc, exec
	v_lshl_add_u32 v192, s30, 8, v206
	v_cndmask_b32_e32 v128, v194, v128, vcc
	s_cselect_b32 s6, s39, s37
	s_cselect_b32 s7, s38, s36
	v_ashrrev_i32_e32 v193, 31, v192
	v_mov_b32_e32 v130, s7
	v_mov_b32_e32 v131, s6
	v_ashrrev_i32_e32 v129, 31, v128
	v_lshl_add_u64 v[196:197], v[192:193], 2, v[130:131]
	v_lshlrev_b64 v[128:129], 12, v[128:129]
	v_lshl_add_u64 v[128:129], v[196:197], 0, v[128:129]
	global_load_dwordx4 v[212:215], v[128:129], off nt
	global_load_dwordx4 v[216:219], v[128:129], off offset:512 nt
	global_load_dwordx4 v[220:223], v[128:129], off offset:16 nt
	global_load_dwordx4 v[224:227], v[128:129], off offset:528 nt
	v_or_b32_e32 v202, 16, v194
	v_add_u32_e32 v128, 0xffffc010, v194
	v_or_b32_e32 v200, 32, v194
	v_add_u32_e32 v129, 0xffffc020, v194
	v_or_b32_e32 v198, 48, v194
	v_add_u32_e32 v131, 0xffffc030, v194
	v_cndmask_b32_e32 v128, v202, v128, vcc
	v_cndmask_b32_e32 v130, v200, v129, vcc
	v_cndmask_b32_e32 v132, v198, v131, vcc
	v_ashrrev_i32_e32 v129, 31, v128
	v_ashrrev_i32_e32 v131, 31, v130
	v_ashrrev_i32_e32 v133, 31, v132
	v_lshlrev_b64 v[128:129], 12, v[128:129]
	v_lshlrev_b64 v[130:131], 12, v[130:131]
	v_lshlrev_b64 v[132:133], 12, v[132:133]
	v_lshl_add_u64 v[128:129], v[196:197], 0, v[128:129]
	v_lshl_add_u64 v[130:131], v[196:197], 0, v[130:131]
	v_lshl_add_u64 v[140:141], v[196:197], 0, v[132:133]
	global_load_dwordx4 v[160:163], v[128:129], off offset:16 nt
	global_load_dwordx4 v[168:171], v[128:129], off nt
	global_load_dwordx4 v[164:167], v[128:129], off offset:528 nt
	global_load_dwordx4 v[172:175], v[128:129], off offset:512 nt
	global_load_dwordx4 v[144:147], v[130:131], off offset:16 nt
	global_load_dwordx4 v[152:155], v[130:131], off nt
	global_load_dwordx4 v[148:151], v[130:131], off offset:528 nt
	global_load_dwordx4 v[156:159], v[130:131], off offset:512 nt
	s_nop 0
	global_load_dwordx4 v[128:131], v[140:141], off offset:16 nt
	global_load_dwordx4 v[136:139], v[140:141], off nt
	global_load_dwordx4 v[132:135], v[140:141], off offset:528 nt
	s_nop 0
	global_load_dwordx4 v[140:143], v[140:141], off offset:512 nt
	v_and_b32_e32 v201, 64, v207
	v_xor_b32_e32 v199, 16, v207
	v_ashrrev_i32_e32 v195, 31, v194
	v_lshlrev_b64 v[228:229], 11, v[194:195]
	v_lshl_add_u64 v[228:229], s[12:13], 0, v[228:229]
	v_lshl_add_u64 v[228:229], v[192:193], 1, v[228:229]
	s_waitcnt vmcnt(0)
	v_add_f32_e32 v124, v124, v212
	v_add_f32_e32 v116, v116, v216
	v_add_f32_e32 v117, v117, v217
	v_add_f32_e32 v125, v125, v213
	v_add_f32_e32 v126, v126, v214
	v_add_f32_e32 v118, v118, v218
	v_add_f32_e32 v127, v127, v215
	v_add_f32_e32 v214, v114, v226
	v_add_f32_e32 v215, v115, v227
	v_mul_f32_e32 v114, v116, v116
	v_mul_f32_e32 v115, v117, v117
	v_add_f32_e32 v119, v119, v219
	v_add_f32_e32 v203, v120, v220
	v_mul_f32_e32 v120, v118, v118
	v_fmac_f32_e32 v114, v124, v124
	v_fmac_f32_e32 v115, v125, v125
	v_add_f32_e32 v211, v112, v224
	v_add_f32_e32 v212, v121, v221
	v_mul_f32_e32 v121, v119, v119
	v_fmac_f32_e32 v120, v126, v126
	v_add_f32_e32 v114, v114, v115
	v_add_f32_e32 v213, v113, v225
	v_mul_f32_e32 v216, v211, v211
	v_fmac_f32_e32 v121, v127, v127
	v_add_f32_e32 v114, v120, v114
	v_mul_f32_e32 v217, v213, v213
	v_fmac_f32_e32 v216, v203, v203
	v_add_f32_e32 v114, v121, v114
	v_add_f32_e32 v122, v122, v222
	v_mul_f32_e32 v218, v214, v214
	v_fmac_f32_e32 v217, v212, v212
	v_add_f32_e32 v114, v216, v114
	v_add_f32_e32 v123, v123, v223
	v_mul_f32_e32 v219, v215, v215
	v_fmac_f32_e32 v218, v122, v122
	v_add_f32_e32 v114, v217, v114
	v_add_u32_e32 v120, 64, v201
	v_fmac_f32_e32 v219, v123, v123
	v_add_f32_e32 v114, v218, v114
	v_cmp_lt_i32_e64 s[6:7], v199, v120
	v_cvt_pk_bf16_f32 v112, v124, v125
	v_add_f32_e32 v124, v219, v114
	v_cvt_pk_bf16_f32 v113, v126, v127
	s_nop 0
	v_cndmask_b32_e64 v114, v207, v199, s[6:7]
	v_lshlrev_b32_e32 v121, 2, v114
	ds_bpermute_b32 v125, v121, v124
	v_cvt_pk_bf16_f32 v114, v203, v212
	v_cvt_pk_bf16_f32 v115, v122, v123
	global_store_dwordx4 v[228:229], v[112:115], off
	s_nop 1
	v_xor_b32_e32 v113, 32, v207
	v_cmp_lt_i32_e64 s[6:7], v113, v120
	s_waitcnt lgkmcnt(0)
	v_add_f32_e32 v112, v124, v125
	v_cvt_pk_bf16_f32 v114, v116, v117
	v_cvt_pk_bf16_f32 v115, v118, v119
	v_cvt_pk_bf16_f32 v116, v211, v213
	v_cvt_pk_bf16_f32 v117, v214, v215
	v_cndmask_b32_e64 v113, v207, v113, s[6:7]
	v_lshlrev_b32_e32 v122, 2, v113
	ds_bpermute_b32 v113, v122, v112
	global_store_dwordx4 v[228:229], v[114:117], off offset:256
	s_and_saveexec_b64 s[6:7], s[0:1]
	s_cbranch_execz .LBB0_2892
	s_waitcnt lgkmcnt(0)
	v_add_f32_e32 v114, v112, v113
	v_lshl_add_u64 v[112:113], v[194:195], 2, s[10:11]
	global_atomic_add_f32 v[112:113], v114, off

; #define EPI_GET(dst, ai, bj, m, s) do { _Pragma("unroll") for (int e_ = 0; e_ < 4; ++e_) { (dst)[e_] = acc[ai][bj][m][0][e_] * (s); (dst)[4 + e_] = acc[ai][bj][m][1][e_] * (s); } } while (0)
;     __device__ __forceinline__ void row(const f32x4 (&acc)[2][2][4][2], int ai, int m, int r, int rl, bool samp, int c8, int fq, const float* a, const float* b) const {
;         float lo[8], hi[8]; EPI_GET(lo, ai, 0, m, 1.f); EPI_GET(hi, ai, 1, m, 1.f);
;         float s2 = 0.f;
; #pragma unroll
;         for (int e = 0; e < 8; ++e) { lo[e] += a[e]; hi[e] += b[e]; s2 += lo[e] * lo[e] + hi[e] * hi[e]; }
;         if (dstP) { float* dp = (samp ? dstS : dstP) + (size_t)rl * 1024 + c8; store8_f32(dp, lo); store8_f32(dp + 128, hi); }
;         if (dstB) { store8_bf16(dstB + (size_t)r * 1024 + c8, lo); store8_bf16(dstB + (size_t)r * 1024 + c8 + 128, hi); }
;         if (ss) { s2 += __shfl_xor(s2, 16); s2 += __shfl_xor(s2, 32); if (fq == 0) atomicAdd(ss + r, s2); }
;     __device__ __forceinline__ void operator()(const f32x4 (&acc)[2][2][4][2], const Unit& u, int wr, int wc, int fr, int fq) const {
;     ...
; #pragma unroll
;             for (int ai = 0; ai < 2; ++ai) {
;                 f32x4 fa[4][2], fb[4][2];
; #pragma unroll
;                 for (int m = 0; m < 4; ++m) { const int r = EPI_ROWS(ai, m); const int rl = samp ? r - MP : r; const float* rp = (samp ? resS : resP) + (size_t)rl * 1024 + c8;
;                     fa[m][0] = *(const f32x4*)rp; fa[m][1] = *(const f32x4*)(rp + 4); fb[m][0] = *(const f32x4*)(rp + 128); fb[m][1] = *(const f32x4*)(rp + 132); }
; #pragma unroll
;                 for (int m = 0; m < 4; ++m) { const int r = EPI_ROWS(ai, m); const int rl = samp ? r - MP : r;
;                     const float a[8] = {fa[m][0].x, fa[m][0].y, fa[m][0].z, fa[m][0].w, fa[m][1].x, fa[m][1].y, fa[m][1].z, fa[m][1].w};
;                     const float b[8] = {fb[m][0].x, fb[m][0].y, fb[m][0].z, fb[m][0].w, fb[m][1].x, fb[m][1].y, fb[m][1].z, fb[m][1].w};
;                     row(acc, ai, m, r, rl, samp, c8, fq, a, b); }
.LBB0_2898:
	s_or_b64 exec, exec, s[6:7]
	v_add_u32_e32 v118, 0x80, v194
	v_add_u32_e32 v64, 0xffffc080, v194
	v_cndmask_b32_e32 v64, v118, v64, vcc
	s_waitcnt lgkmcnt(0)
	v_ashrrev_i32_e32 v65, 31, v64
	v_lshlrev_b64 v[64:65], 12, v[64:65]
	v_lshl_add_u64 v[64:65], v[196:197], 0, v[64:65]
	global_load_dwordx4 v[124:127], v[64:65], off nt
	global_load_dwordx4 v[128:131], v[64:65], off offset:512 nt
	global_load_dwordx4 v[132:135], v[64:65], off offset:16 nt
	global_load_dwordx4 v[136:139], v[64:65], off offset:528 nt
	v_add_u32_e32 v116, 0x90, v194
	v_add_u32_e32 v64, 0xffffc090, v194
	v_add_u32_e32 v114, 0xa0, v194
	v_add_u32_e32 v65, 0xffffc0a0, v194
	v_add_u32_e32 v112, 0xb0, v194
	v_add_u32_e32 v67, 0xffffc0b0, v194
	v_cndmask_b32_e32 v64, v116, v64, vcc
	v_cndmask_b32_e32 v66, v114, v65, vcc
	v_cndmask_b32_e32 v68, v112, v67, vcc
	v_ashrrev_i32_e32 v65, 31, v64
	v_ashrrev_i32_e32 v67, 31, v66
	v_ashrrev_i32_e32 v69, 31, v68
	v_lshlrev_b64 v[64:65], 12, v[64:65]
	v_lshlrev_b64 v[66:67], 12, v[66:67]
	v_lshlrev_b64 v[68:69], 12, v[68:69]
	v_lshl_add_u64 v[64:65], v[196:197], 0, v[64:65]
	v_lshl_add_u64 v[66:67], v[196:197], 0, v[66:67]
	v_lshl_add_u64 v[76:77], v[196:197], 0, v[68:69]
	global_load_dwordx4 v[96:99], v[64:65], off offset:16 nt
	global_load_dwordx4 v[104:107], v[64:65], off nt
	global_load_dwordx4 v[100:103], v[64:65], off offset:528 nt
	global_load_dwordx4 v[108:111], v[64:65], off offset:512 nt
	global_load_dwordx4 v[80:83], v[66:67], off offset:16 nt
	global_load_dwordx4 v[88:91], v[66:67], off nt
	global_load_dwordx4 v[84:87], v[66:67], off offset:528 nt
	global_load_dwordx4 v[92:95], v[66:67], off offset:512 nt
	s_nop 0
	global_load_dwordx4 v[64:67], v[76:77], off offset:16 nt
	global_load_dwordx4 v[72:75], v[76:77], off nt
	global_load_dwordx4 v[68:71], v[76:77], off offset:528 nt
	s_nop 0
	global_load_dwordx4 v[76:79], v[76:77], off offset:512 nt
	v_ashrrev_i32_e32 v119, 31, v118
	v_lshlrev_b64 v[140:141], 11, v[118:119]
	v_lshl_add_u64 v[140:141], s[12:13], 0, v[140:141]
	v_lshl_add_u64 v[140:141], v[192:193], 1, v[140:141]
	s_waitcnt vmcnt(15)
	v_add_f32_e32 v60, v60, v124
	s_waitcnt vmcnt(14)
	v_add_f32_e32 v52, v52, v128
	v_add_f32_e32 v53, v53, v129
	v_add_f32_e32 v61, v61, v125
	v_add_f32_e32 v54, v54, v130
	s_waitcnt vmcnt(12)
	v_add_f32_e32 v115, v49, v137
	v_add_f32_e32 v117, v50, v138
	v_mul_f32_e32 v49, v52, v52
	v_mul_f32_e32 v50, v53, v53
	v_add_f32_e32 v62, v62, v126
	v_add_f32_e32 v55, v55, v131
	v_add_f32_e32 v123, v51, v139
	v_mul_f32_e32 v51, v54, v54
	v_fmac_f32_e32 v49, v60, v60
	v_fmac_f32_e32 v50, v61, v61
	v_add_f32_e32 v63, v63, v127
	v_add_f32_e32 v113, v48, v136
	v_mul_f32_e32 v124, v55, v55
	v_fmac_f32_e32 v51, v62, v62
	v_add_f32_e32 v49, v49, v50
	v_add_f32_e32 v56, v56, v132
	v_mul_f32_e32 v125, v113, v113
	v_fmac_f32_e32 v124, v63, v63
	v_add_f32_e32 v49, v51, v49
	v_add_f32_e32 v57, v57, v133
	v_mul_f32_e32 v126, v115, v115
	v_fmac_f32_e32 v125, v56, v56
	v_add_f32_e32 v49, v124, v49
	v_add_f32_e32 v58, v58, v134
	v_mul_f32_e32 v127, v117, v117
	v_fmac_f32_e32 v126, v57, v57
	v_add_f32_e32 v49, v125, v49
	v_add_f32_e32 v59, v59, v135
	v_mul_f32_e32 v128, v123, v123
	v_fmac_f32_e32 v127, v58, v58
	v_add_f32_e32 v49, v126, v49
	v_fmac_f32_e32 v128, v59, v59
	v_add_f32_e32 v49, v127, v49
	v_cvt_pk_bf16_f32 v48, v60, v61
	v_add_f32_e32 v60, v128, v49
	ds_bpermute_b32 v61, v121, v60
	v_cvt_pk_bf16_f32 v49, v62, v63
	v_cvt_pk_bf16_f32 v50, v56, v57
	v_cvt_pk_bf16_f32 v51, v58, v59
	global_store_dwordx4 v[140:141], v[48:51], off
	s_waitcnt lgkmcnt(0)
	s_nop 0
	v_add_f32_e32 v48, v60, v61
	ds_bpermute_b32 v49, v122, v48
	v_cvt_pk_bf16_f32 v50, v52, v53
	v_cvt_pk_bf16_f32 v51, v54, v55
	v_cvt_pk_bf16_f32 v52, v113, v115
	v_cvt_pk_bf16_f32 v53, v117, v123
	global_store_dwordx4 v[140:141], v[50:53], off offset:256
	s_and_saveexec_b64 s[6:7], s[0:1]
	s_cbranch_execz .LBB0_2900
	s_waitcnt lgkmcnt(0)
	v_add_f32_e32 v50, v48, v49
	v_lshl_add_u64 v[48:49], v[118:119], 2, s[10:11]
	global_atomic_add_f32 v[48:49], v50, off
